# attention: V LDS-DMA after the second PV MFMA group
# speedup vs baseline: 1.0049x; 1.0049x over previous
; #define SBAR() __builtin_amdgcn_sched_barrier(0)
; #define VF_WAIT(N) do { asm volatile("s_waitcnt lgkmcnt(" #N ")" ::: "memory"); SBAR(); } while (0)
; #define A_WAITBAR(N) asm volatile("s_waitcnt vmcnt(" #N ") lgkmcnt(0) ; A256BAR\n\ts_barrier" ::: "memory")
; #define DMA_V(t, sl) do { const char* b_ = Vb + (size_t)(t) * TSTRIDE; const unsigned d_ = RFL(vdst + (sl) * 32768); glds16(b_ + voff[0], d_); glds16(b_ + voff[1], d_ + 1024); glds16(b_ + voff[2], d_ + 2048); glds16(b_ + voff[3], d_ + 3072); } while (0)
; __device__ __forceinline__ void pv8(f32x16* o, int vb, bf16x8 pa0, bf16x8 pa1, bf16x8 pa2, bf16x8 pa3) {
;   VFrag fa, fb; const int vb2 = vb + 16384;
;   vf_read<0>(fa, vb);
;   vf_read<1>(fb, vb);  VF_WAIT(8); vf_mma(o[0], fa, pa0, pa1, pa2, pa3); SBAR();
;   vf_read<2>(fa, vb);  VF_WAIT(8); vf_mma(o[1], fb, pa0, pa1, pa2, pa3); SBAR();
;   vf_read<3>(fb, vb);  VF_WAIT(8); vf_mma(o[2], fa, pa0, pa1, pa2, pa3); SBAR();
;   vf_read<0>(fa, vb2); VF_WAIT(8); vf_mma(o[3], fb, pa0, pa1, pa2, pa3); SBAR();
;   vf_read<1>(fb, vb2); VF_WAIT(8); vf_mma(o[4], fa, pa0, pa1, pa2, pa3); SBAR();
;   vf_read<2>(fa, vb2); VF_WAIT(8); vf_mma(o[5], fb, pa0, pa1, pa2, pa3); SBAR();
;   vf_read<3>(fb, vb2); VF_WAIT(8); vf_mma(o[6], fa, pa0, pa1, pa2, pa3); SBAR();
;   VF_WAIT(0); vf_mma(o[7], fb, pa0, pa1, pa2, pa3);
; }
; template <int mode> ...
;     ...
;     if (more) A_WAITBAR(6); else A_WAITBAR(0);
;     if (more) DMA_V(j + 2, s2);
;     pv8(o, vb0 + s0 * 32768, pa0, pa1, pa2, pa3);
;     if (more) A_WAITBAR(6); else A_WAITBAR(0);
.LBB0_363:
	v_lshl_add_u32 v220, s11, 15, v223
	ds_read_b64_tr_b16 v[144:145], v220 offset:0
	ds_read_b64_tr_b16 v[146:147], v220 offset:0x800
	ds_read_b64_tr_b16 v[148:149], v220 offset:0x1000
	ds_read_b64_tr_b16 v[150:151], v220 offset:0x1800
	ds_read_b64_tr_b16 v[152:153], v220 offset:0x2000
	ds_read_b64_tr_b16 v[154:155], v220 offset:0x2800
	ds_read_b64_tr_b16 v[156:157], v220 offset:0x3000
	ds_read_b64_tr_b16 v[158:159], v220 offset:0x3800
	ds_read_b64_tr_b16 v[194:195], v220 offset:0x200
	ds_read_b64_tr_b16 v[196:197], v220 offset:0xa00
	ds_read_b64_tr_b16 v[214:215], v220 offset:0x1200
	ds_read_b64_tr_b16 v[216:217], v220 offset:0x1a00
	ds_read_b64_tr_b16 v[228:229], v220 offset:0x2200
	ds_read_b64_tr_b16 v[230:231], v220 offset:0x2a00
	ds_read_b64_tr_b16 v[232:233], v220 offset:0x3200
	ds_read_b64_tr_b16 v[234:235], v220 offset:0x3a00
	s_waitcnt lgkmcnt(8)
	v_add_u32_e32 v221, 0x4000, v220
	v_mfma_f32_32x32x16_bf16 v[112:127], v[128:131], v[144:147], v[112:127]
	v_mfma_f32_32x32x16_bf16 v[112:127], v[132:135], v[148:151], v[112:127]
	v_mfma_f32_32x32x16_bf16 v[112:127], v[136:139], v[152:155], v[112:127]
	v_mfma_f32_32x32x16_bf16 v[112:127], v[140:143], v[156:159], v[112:127]
	ds_read_b64_tr_b16 v[144:145], v220 offset:0x400
	ds_read_b64_tr_b16 v[146:147], v220 offset:0xc00
	ds_read_b64_tr_b16 v[148:149], v220 offset:0x1400
	ds_read_b64_tr_b16 v[150:151], v220 offset:0x1c00
	ds_read_b64_tr_b16 v[152:153], v220 offset:0x2400
	ds_read_b64_tr_b16 v[154:155], v220 offset:0x2c00
	ds_read_b64_tr_b16 v[156:157], v220 offset:0x3400
	ds_read_b64_tr_b16 v[158:159], v220 offset:0x3c00
	s_waitcnt lgkmcnt(8)
	v_mfma_f32_32x32x16_bf16 v[96:111], v[128:131], v[194:197], v[96:111]
	v_mfma_f32_32x32x16_bf16 v[96:111], v[132:135], v[214:217], v[96:111]
	v_mfma_f32_32x32x16_bf16 v[96:111], v[136:139], v[228:231], v[96:111]
	v_mfma_f32_32x32x16_bf16 v[96:111], v[140:143], v[232:235], v[96:111]
	ds_read_b64_tr_b16 v[194:195], v220 offset:0x600
	ds_read_b64_tr_b16 v[196:197], v220 offset:0xe00
	ds_read_b64_tr_b16 v[214:215], v220 offset:0x1600
	ds_read_b64_tr_b16 v[216:217], v220 offset:0x1e00
	ds_read_b64_tr_b16 v[228:229], v220 offset:0x2600
	ds_read_b64_tr_b16 v[230:231], v220 offset:0x2e00
	ds_read_b64_tr_b16 v[232:233], v220 offset:0x3600
	ds_read_b64_tr_b16 v[234:235], v220 offset:0x3e00
	s_cbranch_vccnz .Lp0_nodma
	s_lshl_b32 s12, s9, 15
	s_add_i32 s12, s12, s7
	s_mov_b32 s13, m0
	s_mov_b32 m0, s12
	s_nop 0
	global_load_lds_dwordx4 v204, s[38:39]
	s_add_i32 s24, s12, 0x400
	s_mov_b32 m0, s24
	s_nop 0
	global_load_lds_dwordx4 v206, s[38:39]
	s_add_i32 s24, s12, 0x800
	s_mov_b32 m0, s24
	s_nop 0
	global_load_lds_dwordx4 v208, s[38:39]
	s_add_i32 s24, s12, 0xc00
	s_mov_b32 m0, s24
	s_nop 0
	global_load_lds_dwordx4 v210, s[38:39]
	s_mov_b32 m0, s13
.Lp0_nodma:
	s_waitcnt lgkmcnt(8)
	v_mfma_f32_32x32x16_bf16 v[80:95], v[128:131], v[144:147], v[80:95]
	v_mfma_f32_32x32x16_bf16 v[80:95], v[132:135], v[148:151], v[80:95]
	v_mfma_f32_32x32x16_bf16 v[80:95], v[136:139], v[152:155], v[80:95]
	v_mfma_f32_32x32x16_bf16 v[80:95], v[140:143], v[156:159], v[80:95]
	ds_read_b64_tr_b16 v[144:145], v221 offset:0
	ds_read_b64_tr_b16 v[146:147], v221 offset:0x800
	ds_read_b64_tr_b16 v[148:149], v221 offset:0x1000
	ds_read_b64_tr_b16 v[150:151], v221 offset:0x1800
	ds_read_b64_tr_b16 v[152:153], v221 offset:0x2000
	ds_read_b64_tr_b16 v[154:155], v221 offset:0x2800
	ds_read_b64_tr_b16 v[156:157], v221 offset:0x3000
	ds_read_b64_tr_b16 v[158:159], v221 offset:0x3800
	s_waitcnt lgkmcnt(8)
	v_mfma_f32_32x32x16_bf16 v[64:79], v[128:131], v[194:197], v[64:79]
	v_mfma_f32_32x32x16_bf16 v[64:79], v[132:135], v[214:217], v[64:79]
	v_mfma_f32_32x32x16_bf16 v[64:79], v[136:139], v[228:231], v[64:79]
	v_mfma_f32_32x32x16_bf16 v[64:79], v[140:143], v[232:235], v[64:79]
	ds_read_b64_tr_b16 v[194:195], v221 offset:0x200
	ds_read_b64_tr_b16 v[196:197], v221 offset:0xa00
	ds_read_b64_tr_b16 v[214:215], v221 offset:0x1200
	ds_read_b64_tr_b16 v[216:217], v221 offset:0x1a00
	ds_read_b64_tr_b16 v[228:229], v221 offset:0x2200
	ds_read_b64_tr_b16 v[230:231], v221 offset:0x2a00
	ds_read_b64_tr_b16 v[232:233], v221 offset:0x3200
	ds_read_b64_tr_b16 v[234:235], v221 offset:0x3a00
	s_waitcnt lgkmcnt(8)
	v_mfma_f32_32x32x16_bf16 v[48:63], v[128:131], v[144:147], v[48:63]
	v_mfma_f32_32x32x16_bf16 v[48:63], v[132:135], v[148:151], v[48:63]
	v_mfma_f32_32x32x16_bf16 v[48:63], v[136:139], v[152:155], v[48:63]
	v_mfma_f32_32x32x16_bf16 v[48:63], v[140:143], v[156:159], v[48:63]
	ds_read_b64_tr_b16 v[144:145], v221 offset:0x400
	ds_read_b64_tr_b16 v[146:147], v221 offset:0xc00
	ds_read_b64_tr_b16 v[148:149], v221 offset:0x1400
	ds_read_b64_tr_b16 v[150:151], v221 offset:0x1c00
	ds_read_b64_tr_b16 v[152:153], v221 offset:0x2400
	ds_read_b64_tr_b16 v[154:155], v221 offset:0x2c00
	ds_read_b64_tr_b16 v[156:157], v221 offset:0x3400
	ds_read_b64_tr_b16 v[158:159], v221 offset:0x3c00
	s_waitcnt lgkmcnt(8)
	v_mfma_f32_32x32x16_bf16 v[32:47], v[128:131], v[194:197], v[32:47]
	v_mfma_f32_32x32x16_bf16 v[32:47], v[132:135], v[214:217], v[32:47]
	v_mfma_f32_32x32x16_bf16 v[32:47], v[136:139], v[228:231], v[32:47]
	v_mfma_f32_32x32x16_bf16 v[32:47], v[140:143], v[232:235], v[32:47]
	ds_read_b64_tr_b16 v[194:195], v221 offset:0x600
	ds_read_b64_tr_b16 v[196:197], v221 offset:0xe00
	ds_read_b64_tr_b16 v[214:215], v221 offset:0x1600
	ds_read_b64_tr_b16 v[216:217], v221 offset:0x1e00
	ds_read_b64_tr_b16 v[228:229], v221 offset:0x2600
	ds_read_b64_tr_b16 v[230:231], v221 offset:0x2e00
	ds_read_b64_tr_b16 v[232:233], v221 offset:0x3600
	ds_read_b64_tr_b16 v[234:235], v221 offset:0x3e00
	s_waitcnt lgkmcnt(8)
	v_mfma_f32_32x32x16_bf16 v[16:31], v[128:131], v[144:147], v[16:31]
	v_mfma_f32_32x32x16_bf16 v[16:31], v[132:135], v[148:151], v[16:31]
	v_mfma_f32_32x32x16_bf16 v[16:31], v[136:139], v[152:155], v[16:31]
	v_mfma_f32_32x32x16_bf16 v[16:31], v[140:143], v[156:159], v[16:31]
	s_waitcnt lgkmcnt(0)
	v_mfma_f32_32x32x16_bf16 v[0:15], v[128:131], v[194:197], v[0:15]
	s_and_b64 vcc, exec, s[90:91]
	v_mfma_f32_32x32x16_bf16 v[0:15], v[132:135], v[214:217], v[0:15]
	v_mfma_f32_32x32x16_bf16 v[0:15], v[136:139], v[228:231], v[0:15]
	v_mfma_f32_32x32x16_bf16 v[0:15], v[140:143], v[232:235], v[0:15]
	s_cbranch_vccnz .Lm0_ybar0
	s_waitcnt vmcnt(6) lgkmcnt(0)
	s_barrier

; #define SBAR() __builtin_amdgcn_sched_barrier(0)
; #define VF_WAIT(N) do { asm volatile("s_waitcnt lgkmcnt(" #N ")" ::: "memory"); SBAR(); } while (0)
; #define A_WAITBAR(N) asm volatile("s_waitcnt vmcnt(" #N ") lgkmcnt(0) ; A256BAR\n\ts_barrier" ::: "memory")
; #define DMA_V(t, sl) do { const char* b_ = Vb + (size_t)(t) * TSTRIDE; const unsigned d_ = RFL(vdst + (sl) * 32768); glds16(b_ + voff[0], d_); glds16(b_ + voff[1], d_ + 1024); glds16(b_ + voff[2], d_ + 2048); glds16(b_ + voff[3], d_ + 3072); } while (0)
; __device__ __forceinline__ void pv8(f32x16* o, int vb, bf16x8 pa0, bf16x8 pa1, bf16x8 pa2, bf16x8 pa3) {
;   VFrag fa, fb; const int vb2 = vb + 16384;
;   vf_read<0>(fa, vb);
;   vf_read<1>(fb, vb);  VF_WAIT(8); vf_mma(o[0], fa, pa0, pa1, pa2, pa3); SBAR();
;   vf_read<2>(fa, vb);  VF_WAIT(8); vf_mma(o[1], fb, pa0, pa1, pa2, pa3); SBAR();
;   vf_read<3>(fb, vb);  VF_WAIT(8); vf_mma(o[2], fa, pa0, pa1, pa2, pa3); SBAR();
;   vf_read<0>(fa, vb2); VF_WAIT(8); vf_mma(o[3], fb, pa0, pa1, pa2, pa3); SBAR();
;   vf_read<1>(fb, vb2); VF_WAIT(8); vf_mma(o[4], fa, pa0, pa1, pa2, pa3); SBAR();
;   vf_read<2>(fa, vb2); VF_WAIT(8); vf_mma(o[5], fb, pa0, pa1, pa2, pa3); SBAR();
;   vf_read<3>(fb, vb2); VF_WAIT(8); vf_mma(o[6], fa, pa0, pa1, pa2, pa3); SBAR();
;   VF_WAIT(0); vf_mma(o[7], fb, pa0, pa1, pa2, pa3);
; }
; template <int mode> ...
;     ...
;     if (more) A_WAITBAR(6); else A_WAITBAR(0);
;     if (more) DMA_V(j + 2, s2);
;     pv8(o, vb0 + s0 * 32768, pa0, pa1, pa2, pa3);
;     if (more) A_WAITBAR(6); else A_WAITBAR(0);
.LBB0_396:
	v_lshl_add_u32 v231, s10, 15, v226
	ds_read_b64_tr_b16 v[144:145], v231 offset:0
	ds_read_b64_tr_b16 v[146:147], v231 offset:0x800
	ds_read_b64_tr_b16 v[148:149], v231 offset:0x1000
	ds_read_b64_tr_b16 v[150:151], v231 offset:0x1800
	ds_read_b64_tr_b16 v[152:153], v231 offset:0x2000
	ds_read_b64_tr_b16 v[154:155], v231 offset:0x2800
	ds_read_b64_tr_b16 v[156:157], v231 offset:0x3000
	ds_read_b64_tr_b16 v[158:159], v231 offset:0x3800
	ds_read_b64_tr_b16 v[194:195], v231 offset:0x200
	ds_read_b64_tr_b16 v[196:197], v231 offset:0xa00
	ds_read_b64_tr_b16 v[214:215], v231 offset:0x1200
	ds_read_b64_tr_b16 v[216:217], v231 offset:0x1a00
	ds_read_b64_tr_b16 v[220:221], v231 offset:0x2200
	ds_read_b64_tr_b16 v[222:223], v231 offset:0x2a00
	ds_read_b64_tr_b16 v[232:233], v231 offset:0x3200
	ds_read_b64_tr_b16 v[234:235], v231 offset:0x3a00
	s_waitcnt lgkmcnt(8)
	v_add_u32_e32 v236, 0x4000, v231
	v_mfma_f32_32x32x16_bf16 v[16:31], v[128:131], v[144:147], v[16:31]
	v_mfma_f32_32x32x16_bf16 v[16:31], v[132:135], v[148:151], v[16:31]
	v_mfma_f32_32x32x16_bf16 v[16:31], v[136:139], v[152:155], v[16:31]
	v_mfma_f32_32x32x16_bf16 v[16:31], v[140:143], v[156:159], v[16:31]
	ds_read_b64_tr_b16 v[144:145], v231 offset:0x400
	ds_read_b64_tr_b16 v[146:147], v231 offset:0xc00
	ds_read_b64_tr_b16 v[148:149], v231 offset:0x1400
	ds_read_b64_tr_b16 v[150:151], v231 offset:0x1c00
	ds_read_b64_tr_b16 v[152:153], v231 offset:0x2400
	ds_read_b64_tr_b16 v[154:155], v231 offset:0x2c00
	ds_read_b64_tr_b16 v[156:157], v231 offset:0x3400
	ds_read_b64_tr_b16 v[158:159], v231 offset:0x3c00
	s_waitcnt lgkmcnt(8)
	v_mfma_f32_32x32x16_bf16 v[32:47], v[128:131], v[194:197], v[32:47]
	v_mfma_f32_32x32x16_bf16 v[32:47], v[132:135], v[214:217], v[32:47]
	v_mfma_f32_32x32x16_bf16 v[32:47], v[136:139], v[220:223], v[32:47]
	v_mfma_f32_32x32x16_bf16 v[32:47], v[140:143], v[232:235], v[32:47]
	ds_read_b64_tr_b16 v[194:195], v231 offset:0x600
	ds_read_b64_tr_b16 v[196:197], v231 offset:0xe00
	ds_read_b64_tr_b16 v[214:215], v231 offset:0x1600
	ds_read_b64_tr_b16 v[216:217], v231 offset:0x1e00
	ds_read_b64_tr_b16 v[220:221], v231 offset:0x2600
	ds_read_b64_tr_b16 v[222:223], v231 offset:0x2e00
	ds_read_b64_tr_b16 v[232:233], v231 offset:0x3600
	ds_read_b64_tr_b16 v[234:235], v231 offset:0x3e00
	s_cbranch_vccnz .Lp1_nodma
	s_lshl_b32 s11, s7, 15
	s_add_i32 s11, s11, s5
	s_mov_b32 s12, m0
	s_mov_b32 m0, s11
	s_nop 0
	global_load_lds_dwordx4 v204, s[60:61]
	s_add_i32 s13, s11, 0x400
	s_mov_b32 m0, s13
	s_nop 0
	global_load_lds_dwordx4 v206, s[60:61]
	s_add_i32 s13, s11, 0x800
	s_mov_b32 m0, s13
	s_nop 0
	global_load_lds_dwordx4 v208, s[60:61]
	s_add_i32 s13, s11, 0xc00
	s_mov_b32 m0, s13
	s_nop 0
	global_load_lds_dwordx4 v210, s[60:61]
	s_mov_b32 m0, s12
.Lp1_nodma:
	s_waitcnt lgkmcnt(8)
	v_mfma_f32_32x32x16_bf16 v[96:111], v[128:131], v[144:147], v[96:111]
	v_mfma_f32_32x32x16_bf16 v[96:111], v[132:135], v[148:151], v[96:111]
	v_mfma_f32_32x32x16_bf16 v[96:111], v[136:139], v[152:155], v[96:111]
	v_mfma_f32_32x32x16_bf16 v[96:111], v[140:143], v[156:159], v[96:111]
	ds_read_b64_tr_b16 v[144:145], v236 offset:0
	ds_read_b64_tr_b16 v[146:147], v236 offset:0x800
	ds_read_b64_tr_b16 v[148:149], v236 offset:0x1000
	ds_read_b64_tr_b16 v[150:151], v236 offset:0x1800
	ds_read_b64_tr_b16 v[152:153], v236 offset:0x2000
	ds_read_b64_tr_b16 v[154:155], v236 offset:0x2800
	ds_read_b64_tr_b16 v[156:157], v236 offset:0x3000
	ds_read_b64_tr_b16 v[158:159], v236 offset:0x3800
	s_waitcnt lgkmcnt(8)
	v_mfma_f32_32x32x16_bf16 v[112:127], v[128:131], v[194:197], v[112:127]
	v_mfma_f32_32x32x16_bf16 v[112:127], v[132:135], v[214:217], v[112:127]
	v_mfma_f32_32x32x16_bf16 v[112:127], v[136:139], v[220:223], v[112:127]
	v_mfma_f32_32x32x16_bf16 v[112:127], v[140:143], v[232:235], v[112:127]
	ds_read_b64_tr_b16 v[194:195], v236 offset:0x200
	ds_read_b64_tr_b16 v[196:197], v236 offset:0xa00
	ds_read_b64_tr_b16 v[214:215], v236 offset:0x1200
	ds_read_b64_tr_b16 v[216:217], v236 offset:0x1a00
	ds_read_b64_tr_b16 v[220:221], v236 offset:0x2200
	ds_read_b64_tr_b16 v[222:223], v236 offset:0x2a00
	ds_read_b64_tr_b16 v[232:233], v236 offset:0x3200
	ds_read_b64_tr_b16 v[234:235], v236 offset:0x3a00
	s_waitcnt lgkmcnt(8)
	v_mfma_f32_32x32x16_bf16 v[64:79], v[128:131], v[144:147], v[64:79]
	v_mfma_f32_32x32x16_bf16 v[64:79], v[132:135], v[148:151], v[64:79]
	v_mfma_f32_32x32x16_bf16 v[64:79], v[136:139], v[152:155], v[64:79]
	v_mfma_f32_32x32x16_bf16 v[64:79], v[140:143], v[156:159], v[64:79]
	ds_read_b64_tr_b16 v[144:145], v236 offset:0x400
	ds_read_b64_tr_b16 v[146:147], v236 offset:0xc00
	ds_read_b64_tr_b16 v[148:149], v236 offset:0x1400
	ds_read_b64_tr_b16 v[150:151], v236 offset:0x1c00
	ds_read_b64_tr_b16 v[152:153], v236 offset:0x2400
	ds_read_b64_tr_b16 v[154:155], v236 offset:0x2c00
	ds_read_b64_tr_b16 v[156:157], v236 offset:0x3400
	ds_read_b64_tr_b16 v[158:159], v236 offset:0x3c00
	s_waitcnt lgkmcnt(8)
	v_mfma_f32_32x32x16_bf16 v[48:63], v[128:131], v[194:197], v[48:63]
	v_mfma_f32_32x32x16_bf16 v[48:63], v[132:135], v[214:217], v[48:63]
	v_mfma_f32_32x32x16_bf16 v[48:63], v[136:139], v[220:223], v[48:63]
	v_mfma_f32_32x32x16_bf16 v[48:63], v[140:143], v[232:235], v[48:63]
	ds_read_b64_tr_b16 v[194:195], v236 offset:0x600
	ds_read_b64_tr_b16 v[196:197], v236 offset:0xe00
	ds_read_b64_tr_b16 v[214:215], v236 offset:0x1600
	ds_read_b64_tr_b16 v[216:217], v236 offset:0x1e00
	ds_read_b64_tr_b16 v[220:221], v236 offset:0x2600
	ds_read_b64_tr_b16 v[222:223], v236 offset:0x2e00
	ds_read_b64_tr_b16 v[232:233], v236 offset:0x3600
	ds_read_b64_tr_b16 v[234:235], v236 offset:0x3e00
	s_waitcnt lgkmcnt(8)
	v_mfma_f32_32x32x16_bf16 v[0:15], v[128:131], v[144:147], v[0:15]
	v_mfma_f32_32x32x16_bf16 v[0:15], v[132:135], v[148:151], v[0:15]
	v_mfma_f32_32x32x16_bf16 v[0:15], v[136:139], v[152:155], v[0:15]
	v_mfma_f32_32x32x16_bf16 v[0:15], v[140:143], v[156:159], v[0:15]
	s_waitcnt lgkmcnt(0)
	v_mfma_f32_32x32x16_bf16 v[80:95], v[128:131], v[194:197], v[80:95]
	s_and_b64 vcc, exec, s[50:51]
	v_mfma_f32_32x32x16_bf16 v[80:95], v[132:135], v[214:217], v[80:95]
	v_mfma_f32_32x32x16_bf16 v[80:95], v[136:139], v[220:223], v[80:95]
	v_mfma_f32_32x32x16_bf16 v[80:95], v[140:143], v[232:235], v[80:95]
	s_cbranch_vccnz .Lm1_ybar0
	s_waitcnt vmcnt(6) lgkmcnt(0)
	s_barrier
